# attention inner loop: V-fragment LDS reads issued up front into distinct registers with counted lgkmcnt (both sub-tile copies)
# speedup vs baseline: 1.0117x; 1.0117x over previous
; #define LAS __attribute__((address_space(3)))
; #define AT_RAISE(MP) do { if (trig[MP]) { const float dl = fmaxf(__builtin_amdgcn_logf(pmx[MP]), 0.f), al = __builtin_amdgcn_exp2f(-dl); mref[MP] += dl; lsum[MP] *= al; \
;                 _Pragma("unroll") for (int cb = 0; cb < 4; ++cb) o[MP][cb] = o[MP][cb] * al; } } while (0)
; __device__ __forceinline__ void dattn_unit(LAS unsigned char* lds, int b, int h, int qb, const bf16* Q, const bf16* K, const bf16* V, bf16* YB, float lam, const float* subg, float oml, int tid) {
;     ...
;             for (int cb = 0; cb < 4; ++cb) { const LAS bf16* vp = Vt + (32 * cb + ql) * 72 + 32 * sub + 4 * hi;
;                 const v2u a0 = *(const LAS v2u*)(vp), a1 = *(const LAS v2u*)(vp + 8), a2 = *(const LAS v2u*)(vp + 16), a3 = *(const LAS v2u*)(vp + 24);
;                 const v4u f0 = {a0.x, a0.y, a1.x, a1.y}, f1 = {a2.x, a2.y, a3.x, a3.y};
;                 o[0][cb] = __builtin_amdgcn_mfma_f32_32x32x16_bf16(__builtin_bit_cast(bf16x8, f0), pA0, o[0][cb], 0, 0, 0);
;                 o[1][cb] = __builtin_amdgcn_mfma_f32_32x32x16_bf16(__builtin_bit_cast(bf16x8, f0), pA1, o[1][cb], 0, 0, 0);
;                 o[0][cb] = __builtin_amdgcn_mfma_f32_32x32x16_bf16(__builtin_bit_cast(bf16x8, f1), pB0, o[0][cb], 0, 0, 0);
;                 o[1][cb] = __builtin_amdgcn_mfma_f32_32x32x16_bf16(__builtin_bit_cast(bf16x8, f1), pB1, o[1][cb], 0, 0, 0); }
;             AT_RAISE(0); AT_RAISE(1);
.LBB0_234:
	v_add_u32_e32 v141, s38, v193
	v_add_u32_e32 v141, v141, v192
	v_add_u32_e32 v142, 0x5800, v141
	v_add_u32_e32 v143, 0x6800, v141
	v_add_u32_e32 v219, 0x7800, v141
	ds_read2_b64 v[228:231], v142 offset0:64 offset1:66
	ds_read2_b64 v[232:235], v142 offset0:68 offset1:70
	ds_read2_b64 v[236:239], v143 offset0:128 offset1:130
	ds_read2_b64 v[240:243], v143 offset0:132 offset1:134
	ds_read2_b64 v[212:215], v219 offset0:192 offset1:194
	v_cvt_pk_bf16_f32 v224, v201, v202
	v_cvt_pk_bf16_f32 v226, v205, v206
	v_cvt_pk_bf16_f32 v205, v130, v131
	v_cvt_pk_bf16_f32 v206, v132, v156
	v_cvt_pk_bf16_f32 v130, v133, v134
	v_cvt_pk_bf16_f32 v131, v135, v136
	v_cvt_pk_bf16_f32 v132, v137, v138
	v_cvt_pk_bf16_f32 v225, v203, v204
	v_cvt_pk_bf16_f32 v227, v207, v218
	v_cvt_pk_bf16_f32 v204, v155, v129
	v_cvt_pk_bf16_f32 v207, v157, v158
	v_cvt_pk_bf16_f32 v148, v147, v148
	v_cvt_pk_bf16_f32 v149, v149, v150
	v_cvt_pk_bf16_f32 v150, v151, v152
	v_cvt_pk_bf16_f32 v151, v153, v154
	v_cvt_pk_bf16_f32 v133, v139, v140
	v_add_u32_e32 v201, 0x5800, v141
	v_add_u32_e32 v202, 0x6800, v141
	v_add_u32_e32 v203, 0x7800, v141
	v_add_u32_e32 v200, 0x4800, v141
	ds_read2_b64 v[220:223], v200 offset1:2
	ds_read2_b64 v[156:159], v200 offset0:4 offset1:6
	ds_read2_b64 v[134:137], v203 offset0:196 offset1:198
	v_add_f32_e32 v179, v179, v145
	s_andn2_b64 vcc, exec, s[48:49]
	s_waitcnt lgkmcnt(7)
	v_mfma_f32_32x32x16_bf16 v[80:95], v[228:231], v[224:227], v[80:95]
	v_mfma_f32_32x32x16_bf16 v[64:79], v[228:231], v[204:207], v[64:79]
	s_waitcnt lgkmcnt(6)
	v_mfma_f32_32x32x16_bf16 v[80:95], v[232:235], v[148:151], v[80:95]
	v_mfma_f32_32x32x16_bf16 v[64:79], v[232:235], v[130:133], v[64:79]
	s_waitcnt lgkmcnt(5)
	v_mfma_f32_32x32x16_bf16 v[48:63], v[236:239], v[224:227], v[48:63]
	v_mfma_f32_32x32x16_bf16 v[32:47], v[236:239], v[204:207], v[32:47]
	s_waitcnt lgkmcnt(4)
	v_mfma_f32_32x32x16_bf16 v[48:63], v[240:243], v[148:151], v[48:63]
	v_mfma_f32_32x32x16_bf16 v[32:47], v[240:243], v[130:133], v[32:47]
	s_waitcnt lgkmcnt(3)
	v_mfma_f32_32x32x16_bf16 v[16:31], v[212:215], v[224:227], v[16:31]
	v_mfma_f32_32x32x16_bf16 v[0:15], v[212:215], v[204:207], v[0:15]
	s_waitcnt lgkmcnt(2)
	v_mfma_f32_32x32x16_bf16 v[112:127], v[220:223], v[224:227], v[112:127]
	v_mfma_f32_32x32x16_bf16 v[96:111], v[220:223], v[204:207], v[96:111]
	s_waitcnt lgkmcnt(1)
	v_mfma_f32_32x32x16_bf16 v[112:127], v[156:159], v[148:151], v[112:127]
	v_mfma_f32_32x32x16_bf16 v[96:111], v[156:159], v[130:133], v[96:111]
	s_waitcnt lgkmcnt(0)
	v_mfma_f32_32x32x16_bf16 v[16:31], v[134:137], v[148:151], v[16:31]
	v_mfma_f32_32x32x16_bf16 v[0:15], v[134:137], v[130:133], v[0:15]
	s_cbranch_vccnz .LBB0_236
	v_log_f32_e32 v129, v146
	s_nop 0
	v_max_f32_e32 v129, 0, v129
	v_exp_f32_e64 v130, -v129
	v_add_f32_e32 v190, v190, v129
	s_nop 1
	v_pk_mul_f32 v[126:127], v[130:131], v[126:127] op_sel_hi:[0,1]
	v_pk_mul_f32 v[124:125], v[130:131], v[124:125] op_sel_hi:[0,1]
	v_pk_mul_f32 v[122:123], v[130:131], v[122:123] op_sel_hi:[0,1]
	v_pk_mul_f32 v[120:121], v[130:131], v[120:121] op_sel_hi:[0,1]
	v_pk_mul_f32 v[118:119], v[130:131], v[118:119] op_sel_hi:[0,1]
	v_pk_mul_f32 v[116:117], v[130:131], v[116:117] op_sel_hi:[0,1]
	v_pk_mul_f32 v[114:115], v[130:131], v[114:115] op_sel_hi:[0,1]
	v_pk_mul_f32 v[112:113], v[130:131], v[112:113] op_sel_hi:[0,1]
	v_pk_mul_f32 v[94:95], v[130:131], v[94:95] op_sel_hi:[0,1]
	v_pk_mul_f32 v[92:93], v[130:131], v[92:93] op_sel_hi:[0,1]
	v_pk_mul_f32 v[90:91], v[130:131], v[90:91] op_sel_hi:[0,1]
	v_pk_mul_f32 v[88:89], v[130:131], v[88:89] op_sel_hi:[0,1]
	v_pk_mul_f32 v[86:87], v[130:131], v[86:87] op_sel_hi:[0,1]
	v_pk_mul_f32 v[84:85], v[130:131], v[84:85] op_sel_hi:[0,1]
	v_pk_mul_f32 v[82:83], v[130:131], v[82:83] op_sel_hi:[0,1]
	v_pk_mul_f32 v[80:81], v[130:131], v[80:81] op_sel_hi:[0,1]
	v_pk_mul_f32 v[62:63], v[130:131], v[62:63] op_sel_hi:[0,1]
	v_pk_mul_f32 v[60:61], v[130:131], v[60:61] op_sel_hi:[0,1]
	v_pk_mul_f32 v[58:59], v[130:131], v[58:59] op_sel_hi:[0,1]
	v_pk_mul_f32 v[56:57], v[130:131], v[56:57] op_sel_hi:[0,1]
	v_pk_mul_f32 v[54:55], v[130:131], v[54:55] op_sel_hi:[0,1]
	v_pk_mul_f32 v[52:53], v[130:131], v[52:53] op_sel_hi:[0,1]
	v_pk_mul_f32 v[50:51], v[130:131], v[50:51] op_sel_hi:[0,1]
	v_pk_mul_f32 v[48:49], v[130:131], v[48:49] op_sel_hi:[0,1]
	v_pk_mul_f32 v[30:31], v[130:131], v[30:31] op_sel_hi:[0,1]
	v_pk_mul_f32 v[28:29], v[130:131], v[28:29] op_sel_hi:[0,1]
	v_pk_mul_f32 v[26:27], v[130:131], v[26:27] op_sel_hi:[0,1]
	v_pk_mul_f32 v[24:25], v[130:131], v[24:25] op_sel_hi:[0,1]
	v_pk_mul_f32 v[22:23], v[130:131], v[22:23] op_sel_hi:[0,1]
	v_pk_mul_f32 v[20:21], v[130:131], v[20:21] op_sel_hi:[0,1]
	v_pk_mul_f32 v[18:19], v[130:131], v[18:19] op_sel_hi:[0,1]
	v_pk_mul_f32 v[16:17], v[130:131], v[16:17] op_sel_hi:[0,1]
	v_mul_f32_e32 v179, v179, v130

; #define LAS __attribute__((address_space(3)))
; #define AT_RAISE(MP) do { if (trig[MP]) { const float dl = fmaxf(__builtin_amdgcn_logf(pmx[MP]), 0.f), al = __builtin_amdgcn_exp2f(-dl); mref[MP] += dl; lsum[MP] *= al; \
;                 _Pragma("unroll") for (int cb = 0; cb < 4; ++cb) o[MP][cb] = o[MP][cb] * al; } } while (0)
; __device__ __forceinline__ void dattn_unit(LAS unsigned char* lds, int b, int h, int qb, const bf16* Q, const bf16* K, const bf16* V, bf16* YB, float lam, const float* subg, float oml, int tid) {
;     ...
;             for (int cb = 0; cb < 4; ++cb) { const LAS bf16* vp = Vt + (32 * cb + ql) * 72 + 32 * sub + 4 * hi;
;                 const v2u a0 = *(const LAS v2u*)(vp), a1 = *(const LAS v2u*)(vp + 8), a2 = *(const LAS v2u*)(vp + 16), a3 = *(const LAS v2u*)(vp + 24);
;                 const v4u f0 = {a0.x, a0.y, a1.x, a1.y}, f1 = {a2.x, a2.y, a3.x, a3.y};
;                 o[0][cb] = __builtin_amdgcn_mfma_f32_32x32x16_bf16(__builtin_bit_cast(bf16x8, f0), pA0, o[0][cb], 0, 0, 0);
;                 o[1][cb] = __builtin_amdgcn_mfma_f32_32x32x16_bf16(__builtin_bit_cast(bf16x8, f0), pA1, o[1][cb], 0, 0, 0);
;                 o[0][cb] = __builtin_amdgcn_mfma_f32_32x32x16_bf16(__builtin_bit_cast(bf16x8, f1), pB0, o[0][cb], 0, 0, 0);
;                 o[1][cb] = __builtin_amdgcn_mfma_f32_32x32x16_bf16(__builtin_bit_cast(bf16x8, f1), pB1, o[1][cb], 0, 0, 0); }
;             AT_RAISE(0); AT_RAISE(1);
.LBB0_245:
	ds_read2_b64 v[222:225], v201 offset0:72 offset1:74
	ds_read2_b64 v[226:229], v201 offset0:76 offset1:78
	ds_read2_b64 v[230:233], v202 offset0:136 offset1:138
	ds_read2_b64 v[234:237], v202 offset0:140 offset1:142
	ds_read2_b64 v[238:241], v203 offset0:200 offset1:202
	ds_read2_b64 v[212:215], v200 offset0:8 offset1:10
	v_cvt_pk_bf16_f32 v205, v205, v206
	v_cvt_pk_bf16_f32 v206, v207, v218
	v_cvt_pk_bf16_f32 v207, v219, v220
	v_cvt_pk_bf16_f32 v219, v130, v131
	v_cvt_pk_bf16_f32 v220, v132, v156
	v_cvt_pk_bf16_f32 v130, v133, v134
	v_cvt_pk_bf16_f32 v131, v135, v136
	v_cvt_pk_bf16_f32 v132, v137, v138
	v_cvt_pk_bf16_f32 v204, v199, v204
	v_cvt_pk_bf16_f32 v218, v155, v129
	v_cvt_pk_bf16_f32 v221, v157, v158
	v_cvt_pk_bf16_f32 v148, v147, v148
	v_cvt_pk_bf16_f32 v149, v149, v150
	v_cvt_pk_bf16_f32 v150, v151, v152
	v_cvt_pk_bf16_f32 v151, v153, v154
	v_cvt_pk_bf16_f32 v133, v139, v140
	ds_read2_b64 v[156:159], v200 offset0:12 offset1:14
	ds_read2_b64 v[134:137], v203 offset0:204 offset1:206
	v_add_f32_e32 v179, v179, v145
	s_andn2_b64 vcc, exec, s[48:49]
	s_waitcnt lgkmcnt(7)
	v_mfma_f32_32x32x16_bf16 v[80:95], v[222:225], v[204:207], v[80:95]
	v_mfma_f32_32x32x16_bf16 v[64:79], v[222:225], v[218:221], v[64:79]
	s_waitcnt lgkmcnt(6)
	v_mfma_f32_32x32x16_bf16 v[80:95], v[226:229], v[148:151], v[80:95]
	v_mfma_f32_32x32x16_bf16 v[64:79], v[226:229], v[130:133], v[64:79]
	s_waitcnt lgkmcnt(5)
	v_mfma_f32_32x32x16_bf16 v[48:63], v[230:233], v[204:207], v[48:63]
	v_mfma_f32_32x32x16_bf16 v[32:47], v[230:233], v[218:221], v[32:47]
	s_waitcnt lgkmcnt(4)
	v_mfma_f32_32x32x16_bf16 v[48:63], v[234:237], v[148:151], v[48:63]
	v_mfma_f32_32x32x16_bf16 v[32:47], v[234:237], v[130:133], v[32:47]
	s_waitcnt lgkmcnt(3)
	v_mfma_f32_32x32x16_bf16 v[16:31], v[238:241], v[204:207], v[16:31]
	v_mfma_f32_32x32x16_bf16 v[0:15], v[238:241], v[218:221], v[0:15]
	s_waitcnt lgkmcnt(2)
	v_mfma_f32_32x32x16_bf16 v[112:127], v[212:215], v[204:207], v[112:127]
	v_mfma_f32_32x32x16_bf16 v[96:111], v[212:215], v[218:221], v[96:111]
	s_waitcnt lgkmcnt(1)
	v_mfma_f32_32x32x16_bf16 v[112:127], v[156:159], v[148:151], v[112:127]
	v_mfma_f32_32x32x16_bf16 v[96:111], v[156:159], v[130:133], v[96:111]
	s_waitcnt lgkmcnt(0)
	v_mfma_f32_32x32x16_bf16 v[16:31], v[134:137], v[148:151], v[16:31]
	v_mfma_f32_32x32x16_bf16 v[0:15], v[134:137], v[130:133], v[0:15]
	s_cbranch_vccnz .LBB0_247
	v_log_f32_e32 v129, v146
	s_nop 0
	v_max_f32_e32 v129, 0, v129
	v_exp_f32_e64 v130, -v129
	v_add_f32_e32 v190, v190, v129
	s_nop 1
	v_pk_mul_f32 v[126:127], v[130:131], v[126:127] op_sel_hi:[0,1]
	v_pk_mul_f32 v[124:125], v[130:131], v[124:125] op_sel_hi:[0,1]
	v_pk_mul_f32 v[122:123], v[130:131], v[122:123] op_sel_hi:[0,1]
	v_pk_mul_f32 v[120:121], v[130:131], v[120:121] op_sel_hi:[0,1]
	v_pk_mul_f32 v[118:119], v[130:131], v[118:119] op_sel_hi:[0,1]
	v_pk_mul_f32 v[116:117], v[130:131], v[116:117] op_sel_hi:[0,1]
	v_pk_mul_f32 v[114:115], v[130:131], v[114:115] op_sel_hi:[0,1]
	v_pk_mul_f32 v[112:113], v[130:131], v[112:113] op_sel_hi:[0,1]
	v_pk_mul_f32 v[94:95], v[130:131], v[94:95] op_sel_hi:[0,1]
	v_pk_mul_f32 v[92:93], v[130:131], v[92:93] op_sel_hi:[0,1]
	v_pk_mul_f32 v[90:91], v[130:131], v[90:91] op_sel_hi:[0,1]
	v_pk_mul_f32 v[88:89], v[130:131], v[88:89] op_sel_hi:[0,1]
	v_pk_mul_f32 v[86:87], v[130:131], v[86:87] op_sel_hi:[0,1]
	v_pk_mul_f32 v[84:85], v[130:131], v[84:85] op_sel_hi:[0,1]
	v_pk_mul_f32 v[82:83], v[130:131], v[82:83] op_sel_hi:[0,1]
	v_pk_mul_f32 v[80:81], v[130:131], v[80:81] op_sel_hi:[0,1]
	v_pk_mul_f32 v[62:63], v[130:131], v[62:63] op_sel_hi:[0,1]
	v_pk_mul_f32 v[60:61], v[130:131], v[60:61] op_sel_hi:[0,1]
	v_pk_mul_f32 v[58:59], v[130:131], v[58:59] op_sel_hi:[0,1]
	v_pk_mul_f32 v[56:57], v[130:131], v[56:57] op_sel_hi:[0,1]
	v_pk_mul_f32 v[54:55], v[130:131], v[54:55] op_sel_hi:[0,1]
	v_pk_mul_f32 v[52:53], v[130:131], v[52:53] op_sel_hi:[0,1]
	v_pk_mul_f32 v[50:51], v[130:131], v[50:51] op_sel_hi:[0,1]
	v_pk_mul_f32 v[48:49], v[130:131], v[48:49] op_sel_hi:[0,1]
	v_pk_mul_f32 v[30:31], v[130:131], v[30:31] op_sel_hi:[0,1]
	v_pk_mul_f32 v[28:29], v[130:131], v[28:29] op_sel_hi:[0,1]
	v_pk_mul_f32 v[26:27], v[130:131], v[26:27] op_sel_hi:[0,1]
	v_pk_mul_f32 v[24:25], v[130:131], v[24:25] op_sel_hi:[0,1]
	v_pk_mul_f32 v[22:23], v[130:131], v[22:23] op_sel_hi:[0,1]
	v_pk_mul_f32 v[20:21], v[130:131], v[20:21] op_sel_hi:[0,1]
	v_pk_mul_f32 v[18:19], v[130:131], v[18:19] op_sel_hi:[0,1]
	v_pk_mul_f32 v[16:17], v[130:131], v[16:17] op_sel_hi:[0,1]
	v_mul_f32_e32 v179, v179, v130
